# v22 + hand-written software-pipelined weight-conversion loop (two items of loads in flight) with write-through stores
# baseline (speedup 1.0000x reference)
; #define LAS __attribute__((address_space(3)))
; __device__ __forceinline__ unsigned pk2(float lo, float hi) { return f2bf(lo) | (f2bf(hi) << 16); }
; __device__ __forceinline__ void tr_item(const float* W, int K, int N, const float* kscale, bf16* WT, int dst_row0, LAS float* scr, int k0, int n0, int lane) {
;     ...
;     for (int j = 0; j < 4; ++j) { const int n = (lane >> 3) + 8 * j; const LAS float* s = scr + (8 * c) * 33 + n;
;         u32x4 o; o.x = pk2(s[0 * 33], s[1 * 33]); o.y = pk2(s[2 * 33], s[3 * 33]); o.z = pk2(s[4 * 33], s[5 * 33]); o.w = pk2(s[6 * 33], s[7 * 33]);
;         *(u32x4*)(WT + (size_t)(dst_row0 + n) * K + k0 + 8 * c) = o; }
; __device__ __forceinline__ void prologue(const Args& a, LAS unsigned char* lds, int wave, int lane) {
;     ...
;     for (int it = gw; it < DEPTH * I_L; it += NGW) {
.Lwq_nks_2:
	v_cvt_pk_bf16_f32 v58, v26, v28
	v_cvt_pk_bf16_f32 v59, v30, v32
	v_cvt_pk_bf16_f32 v60, v34, v36
	v_cvt_pk_bf16_f32 v61, v38, v40
	v_cvt_pk_bf16_f32 v62, v27, v29
	v_cvt_pk_bf16_f32 v63, v31, v33
	v_cvt_pk_bf16_f32 v64, v35, v37
	v_cvt_pk_bf16_f32 v65, v39, v41
	v_cvt_pk_bf16_f32 v66, v42, v44
	v_cvt_pk_bf16_f32 v67, v46, v48
	v_cvt_pk_bf16_f32 v68, v50, v52
	v_cvt_pk_bf16_f32 v69, v54, v56
	v_cvt_pk_bf16_f32 v70, v43, v45
	v_cvt_pk_bf16_f32 v71, v47, v49
	v_cvt_pk_bf16_f32 v72, v51, v53
	v_cvt_pk_bf16_f32 v73, v55, v57
	global_store_dwordx4 v22, v[58:61], s[68:69] sc0 sc1
	global_store_dwordx4 v23, v[62:65], s[68:69] sc0 sc1
	global_store_dwordx4 v24, v[66:69], s[68:69] sc0 sc1
	global_store_dwordx4 v25, v[70:73], s[68:69] sc0 sc1
	s_cmp_lt_u32 s82, 0x5100
	s_cbranch_scc0 .LBB0_81
	s_mov_b32 s83, s82

; #define LAS __attribute__((address_space(3)))
; __device__ __forceinline__ unsigned pk2(float lo, float hi) { return f2bf(lo) | (f2bf(hi) << 16); }
; __device__ __forceinline__ void tr_item(const float* W, int K, int N, const float* kscale, bf16* WT, int dst_row0, LAS float* scr, int k0, int n0, int lane) {
;     ...
;     for (int j = 0; j < 4; ++j) { const int n = (lane >> 3) + 8 * j; const LAS float* s = scr + (8 * c) * 33 + n;
;         u32x4 o; o.x = pk2(s[0 * 33], s[1 * 33]); o.y = pk2(s[2 * 33], s[3 * 33]); o.z = pk2(s[4 * 33], s[5 * 33]); o.w = pk2(s[6 * 33], s[7 * 33]);
;         *(u32x4*)(WT + (size_t)(dst_row0 + n) * K + k0 + 8 * c) = o; }
; __device__ __forceinline__ void prologue(const Args& a, LAS unsigned char* lds, int wave, int lane) {
;     ...
;     for (int it = gw; it < DEPTH * I_L; it += NGW) {
.Lwq_nks_4:
	v_cvt_pk_bf16_f32 v58, v26, v28
	v_cvt_pk_bf16_f32 v59, v30, v32
	v_cvt_pk_bf16_f32 v60, v34, v36
	v_cvt_pk_bf16_f32 v61, v38, v40
	v_cvt_pk_bf16_f32 v62, v27, v29
	v_cvt_pk_bf16_f32 v63, v31, v33
	v_cvt_pk_bf16_f32 v64, v35, v37
	v_cvt_pk_bf16_f32 v65, v39, v41
	v_cvt_pk_bf16_f32 v66, v42, v44
	v_cvt_pk_bf16_f32 v67, v46, v48
	v_cvt_pk_bf16_f32 v68, v50, v52
	v_cvt_pk_bf16_f32 v69, v54, v56
	v_cvt_pk_bf16_f32 v70, v43, v45
	v_cvt_pk_bf16_f32 v71, v47, v49
	v_cvt_pk_bf16_f32 v72, v51, v53
	v_cvt_pk_bf16_f32 v73, v55, v57
	global_store_dwordx4 v22, v[58:61], s[78:79] sc0 sc1
	global_store_dwordx4 v23, v[62:65], s[78:79] sc0 sc1
	global_store_dwordx4 v24, v[66:69], s[78:79] sc0 sc1
	global_store_dwordx4 v25, v[70:73], s[78:79] sc0 sc1
	s_cmp_lt_u32 s82, 0x5100
	s_cbranch_scc0 .LBB0_81
	s_mov_b32 s83, s82
	s_branch .Lwq_top0
